# delta-rule scan chunk loop hand-scheduled: fragments prefetched into rotating register groups, interleaved accumulator chains, stores under the MFMAs
# speedup vs baseline: 1.0435x; 1.0001x over previous
.LBB0_222:
	s_and_b64 s[6:7], exec, s[4:5]
	s_cselect_b32 s6, s10, s25
	s_lshl_b32 s6, s6, 10
	s_addk_i32 s6, 0x1000
	s_lshl_b32 s7, s25, 8
	s_and_b64 s[4:5], exec, s[4:5]
	s_cselect_b32 s38, 16, 4
	s_cselect_b32 s10, s6, s7
	s_add_i32 s11, s38, -1
	s_cmp_eq_u32 s27, 0
	s_cselect_b64 s[4:5], -1, 0
	s_and_b64 s[6:7], s[4:5], exec
	s_cselect_b32 s6, 0, s11
	s_ashr_i32 s39, s10, 6
	s_add_i32 s6, s39, s6
	s_lshl_b32 s6, s6, 3
	s_lshl_b32 s7, s22, 1
	s_or_b32 s6, s6, s7
	v_and_b32_e32 v79, 63, v2
	s_or_b32 s6, s6, s27
	v_lshrrev_b32_e32 v6, 3, v79
	s_ashr_i32 s7, s6, 31
	s_mul_i32 s10, s6, 0xc000
	v_lshlrev_b32_e32 v7, 7, v6
	v_bitop3_b32 v6, v6, v2, 7 bitop3:0x78
	s_mul_hi_i32 s11, s6, 0xc000
	s_add_u32 s10, s68, s10
	v_lshl_or_b32 v74, v6, 4, v7
	s_addc_u32 s11, s69, s11
	v_lshlrev_b32_e32 v76, 13, v5
	v_mov_b32_e32 v75, v131
	v_lshl_add_u64 v[6:7], s[10:11], 0, v[74:75]
	s_mov_b64 s[36:37], 0x4000
	v_add_u32_e32 v27, 0, v76
	v_lshl_add_u64 v[6:7], v[6:7], 0, s[36:37]
	v_ashrrev_i32_e32 v77, 31, v76
	v_readfirstlane_b32 s36, v27
	v_add_u32_e32 v5, 0x400, v27
	v_lshl_add_u64 v[8:9], v[6:7], 0, v[76:77]
	s_mov_b32 m0, s36
	v_readfirstlane_b32 s36, v5
	s_waitcnt vmcnt(63) expcnt(7) lgkmcnt(15)
	s_barrier
	global_load_lds_dwordx4 v[8:9], off
	v_lshl_add_u64 v[10:11], v[8:9], 0, s[90:91]
	s_mov_b32 m0, s36
	s_mov_b64 s[36:37], 0x800
	v_add_u32_e32 v5, 0x800, v27
	global_load_lds_dwordx4 v[10:11], off
	v_lshl_add_u64 v[10:11], v[8:9], 0, s[36:37]
	v_readfirstlane_b32 s36, v5
	s_mov_b32 m0, s36
	s_mov_b64 s[36:37], 0xc00
	v_add_u32_e32 v5, 0xc00, v27
	v_lshl_add_u64 v[8:9], v[8:9], 0, s[36:37]
	v_readfirstlane_b32 s36, v5
	v_or_b32_e32 v80, 0x1000, v76
	v_add_u32_e32 v5, 0x1000, v27
	global_load_lds_dwordx4 v[10:11], off
	s_mov_b32 m0, s36
	v_ashrrev_i32_e32 v81, 31, v80
	v_readfirstlane_b32 s36, v5
	v_or_b32_e32 v82, 0x1400, v76
	v_add_u32_e32 v5, 0x1400, v27
	global_load_lds_dwordx4 v[8:9], off
	v_lshl_add_u64 v[8:9], v[6:7], 0, v[80:81]
	s_mov_b32 m0, s36
	v_ashrrev_i32_e32 v83, 31, v82
	v_readfirstlane_b32 s36, v5
	v_or_b32_e32 v84, 0x1800, v76
	v_add_u32_e32 v5, 0x1800, v27
	global_load_lds_dwordx4 v[8:9], off
	v_lshl_add_u64 v[8:9], v[6:7], 0, v[82:83]
	s_mov_b32 m0, s36
	v_ashrrev_i32_e32 v85, 31, v84
	v_readfirstlane_b32 s36, v5
	v_or_b32_e32 v88, 0x1c00, v76
	v_add_u32_e32 v5, 0x1c00, v27
	global_load_lds_dwordx4 v[8:9], off
	v_lshl_add_u64 v[8:9], v[6:7], 0, v[84:85]
	s_mov_b32 m0, s36
	v_ashrrev_i32_e32 v89, 31, v88
	v_readfirstlane_b32 s36, v5
	v_ashrrev_i32_e32 v23, 31, v22
	global_load_lds_dwordx4 v[8:9], off
	v_lshl_add_u64 v[6:7], v[6:7], 0, v[88:89]
	s_mov_b32 m0, s36
	v_lshlrev_b64 v[86:87], 2, v[22:23]
	global_load_lds_dwordx4 v[6:7], off
	v_lshl_add_u64 v[6:7], s[10:11], 0, v[86:87]
	v_lshlrev_b32_e32 v130, 2, v26
	v_mov_b32_e32 v49, v131
	v_lshl_add_u64 v[8:9], v[6:7], 0, v[130:131]
	v_mov_b32_e32 v57, v131
	v_mov_b32_e32 v55, v131
	v_mov_b32_e32 v53, v131
	v_mov_b32_e32 v51, v131
	v_lshl_add_u64 v[20:21], v[48:49], 2, v[6:7]
	v_mov_b32_e32 v47, v131
	v_mov_b32_e32 v45, v131
	v_mov_b32_e32 v43, v131
	v_lshl_add_u64 v[10:11], v[56:57], 2, v[6:7]
	v_lshl_add_u64 v[12:13], v[54:55], 2, v[6:7]
	v_lshl_add_u64 v[14:15], v[52:53], 2, v[6:7]
	v_lshl_add_u64 v[16:17], v[50:51], 2, v[6:7]
	v_lshl_add_u64 v[90:91], v[46:47], 2, v[6:7]
	v_lshl_add_u64 v[92:93], v[44:45], 2, v[6:7]
	global_load_dword v138, v[8:9], off
	global_load_dword v139, v[10:11], off
	global_load_dword v140, v[12:13], off
	global_load_dword v141, v[14:15], off
	global_load_dword v18, v[16:17], off
	global_load_dword v19, v[20:21], off
	s_nop 0
	global_load_dword v20, v[90:91], off
	global_load_dword v21, v[92:93], off
	v_lshl_add_u64 v[8:9], v[42:43], 2, v[6:7]
	v_mov_b32_e32 v41, v131
	v_mov_b32_e32 v39, v131
	v_mov_b32_e32 v37, v131
	v_mov_b32_e32 v35, v131
	v_mov_b32_e32 v33, v131
	v_mov_b32_e32 v31, v131
	v_mov_b32_e32 v29, v131
	v_lshl_add_u64 v[10:11], v[40:41], 2, v[6:7]
	v_lshl_add_u64 v[12:13], v[38:39], 2, v[6:7]
	v_lshl_add_u64 v[14:15], v[36:37], 2, v[6:7]
	v_lshl_add_u64 v[16:17], v[34:35], 2, v[6:7]
	v_lshl_add_u64 v[90:91], v[32:33], 2, v[6:7]
	v_lshl_add_u64 v[92:93], v[30:31], 2, v[6:7]
	v_lshl_add_u64 v[6:7], v[28:29], 2, v[6:7]
	global_load_dword v132, v[8:9], off
	global_load_dword v134, v[10:11], off
	global_load_dword v136, v[12:13], off
	global_load_dword v137, v[14:15], off
	global_load_dword v120, v[16:17], off
	global_load_dword v123, v[90:91], off
	global_load_dword v125, v[92:93], off
	global_load_dword v126, v[6:7], off
	s_mov_b64 s[100:101], s[6:7]
	s_lshl_b64 s[6:7], s[6:7], 2
	s_add_u32 s6, s86, s6
	s_addc_u32 s7, s87, s7
	global_load_dword v94, v131, s[6:7]
	v_lshlrev_b32_e32 v4, 7, v4
	v_lshlrev_b32_e32 v3, 3, v3
	v_and_or_b32 v3, v3, 8, v4
	v_lshrrev_b32_e32 v4, 5, v79
	v_and_b32_e32 v5, 7, v2
	v_bitop3_b32 v2, v4, v2, 7 bitop3:0x78
	v_lshlrev_b32_e32 v23, 4, v2
	v_bitop3_b32 v2, v4, v5, 2 bitop3:0x36
	s_waitcnt vmcnt(0)
	v_readlane_b32 s6, v253, 24
	v_lshlrev_b32_e32 v95, 4, v2
	v_bitop3_b32 v2, v4, v5, 4 bitop3:0x36
	v_readlane_b32 s7, v253, 25
	v_lshlrev_b32_e32 v110, 4, v2
	v_bitop3_b32 v2, v4, v5, 6 bitop3:0x36
	s_mov_b32 s40, 0
	s_add_i32 s41, s38, 0x1ffffffe
	v_lshl_add_u64 v[90:91], s[68:69], 0, v[86:87]
	v_lshl_add_u64 v[92:93], s[6:7], 0, v[86:87]
	v_lshlrev_b32_e32 v111, 4, v2
	s_and_b32 s42, s42, 7
	v_add_u32_e32 v112, 0, v3
	s_mov_b64 s[6:7], 0
	s_mov_b32 s45, 0
	v_mov_b32_e32 v79, v78
	v_mov_b32_e32 v102, v78
	v_mov_b32_e32 v103, v78
	v_mov_b32_e32 v106, v78
	v_mov_b32_e32 v107, v78
	v_mov_b32_e32 v98, v78
	v_mov_b32_e32 v99, v78
	v_mov_b32_e32 v108, v78
	v_mov_b32_e32 v109, v78
	v_mov_b32_e32 v100, v78
	v_mov_b32_e32 v101, v78
	v_mov_b32_e32 v104, v78
	v_mov_b32_e32 v105, v78
	v_mov_b32_e32 v96, v78
	v_mov_b32_e32 v97, v78
	s_waitcnt vmcnt(0) lgkmcnt(0)
	s_barrier
	v_mov_b32_e32 v159, v60
	v_mov_b32_e32 v158, v61
	v_mov_b32_e32 v157, v58
	v_mov_b32_e32 v156, v59
	v_mov_b32_e32 v155, v62
	v_mov_b32_e32 v154, v63
	v_mov_b32_e32 v153, v64
	v_mov_b32_e32 v152, v65
	v_mov_b32_e32 v151, v66
	v_mov_b32_e32 v150, v67
	v_mov_b32_e32 v149, v68
	v_mov_b32_e32 v148, v69
	v_mov_b32_e32 v147, v70
	v_mov_b32_e32 v146, v71
	v_mov_b32_e32 v145, v72
	v_mov_b32_e32 v144, v73
	v_mov_b32_e32 v78, v138
	v_mov_b32_e32 v79, v139
	v_mov_b32_e32 v102, v140
	v_mov_b32_e32 v103, v141
	v_mov_b32_e32 v106, v18
	v_mov_b32_e32 v107, v19
	v_mov_b32_e32 v98, v20
	v_mov_b32_e32 v99, v21
	v_mov_b32_e32 v108, v132
	v_mov_b32_e32 v109, v134
	v_mov_b32_e32 v100, v136
	v_mov_b32_e32 v101, v137
	v_mov_b32_e32 v104, v120
	v_mov_b32_e32 v105, v123
	v_mov_b32_e32 v96, v125
	v_mov_b32_e32 v97, v126
	s_mov_b64 s[6:7], s[100:101]
	v_lshlrev_b32_e32 v196, 2, v24
	v_add_u32_e32 v205, 0x1000, v196
	v_add_u32_e32 v201, 0x2000, v196
	v_add_u32_e32 v202, 0x3000, v196
	v_and_b32_sdwa v239, v61, v1 dst_sel:DWORD dst_unused:UNUSED_PAD src0_sel:WORD_1 src1_sel:DWORD
	v_and_b32_sdwa v238, v60, v1 dst_sel:DWORD dst_unused:UNUSED_PAD src0_sel:WORD_1 src1_sel:DWORD
	v_add3_u32 v239, v61, v239, s26
	v_add3_u32 v238, v60, v238, s26
	v_and_b32_e32 v239, 0xffff0000, v239
	v_or_b32_sdwa v222, v239, v238 dst_sel:DWORD dst_unused:UNUSED_PAD src0_sel:DWORD src1_sel:WORD_1
	v_and_b32_e32 v238, 0xffff0000, v238
	v_pk_add_f32 v[240:241], v[60:61], v[238:239] neg_lo:[0,1] neg_hi:[0,1]
	v_cvt_pk_bf16_f32 v226, v240, v241
	v_and_b32_sdwa v243, v59, v1 dst_sel:DWORD dst_unused:UNUSED_PAD src0_sel:WORD_1 src1_sel:DWORD
	v_and_b32_sdwa v242, v58, v1 dst_sel:DWORD dst_unused:UNUSED_PAD src0_sel:WORD_1 src1_sel:DWORD
	v_add3_u32 v243, v59, v243, s26
	v_add3_u32 v242, v58, v242, s26
	v_and_b32_e32 v243, 0xffff0000, v243
	v_or_b32_sdwa v223, v243, v242 dst_sel:DWORD dst_unused:UNUSED_PAD src0_sel:DWORD src1_sel:WORD_1
	v_and_b32_e32 v242, 0xffff0000, v242
	v_pk_add_f32 v[244:245], v[58:59], v[242:243] neg_lo:[0,1] neg_hi:[0,1]
	v_cvt_pk_bf16_f32 v227, v244, v245
	v_and_b32_sdwa v247, v63, v1 dst_sel:DWORD dst_unused:UNUSED_PAD src0_sel:WORD_1 src1_sel:DWORD
	v_and_b32_sdwa v246, v62, v1 dst_sel:DWORD dst_unused:UNUSED_PAD src0_sel:WORD_1 src1_sel:DWORD
	v_add3_u32 v247, v63, v247, s26
	v_add3_u32 v246, v62, v246, s26
	v_and_b32_e32 v247, 0xffff0000, v247
	v_or_b32_sdwa v224, v247, v246 dst_sel:DWORD dst_unused:UNUSED_PAD src0_sel:DWORD src1_sel:WORD_1
	v_and_b32_e32 v246, 0xffff0000, v246
	v_pk_add_f32 v[248:249], v[62:63], v[246:247] neg_lo:[0,1] neg_hi:[0,1]
	v_cvt_pk_bf16_f32 v228, v248, v249
	v_and_b32_sdwa v239, v65, v1 dst_sel:DWORD dst_unused:UNUSED_PAD src0_sel:WORD_1 src1_sel:DWORD
	v_and_b32_sdwa v238, v64, v1 dst_sel:DWORD dst_unused:UNUSED_PAD src0_sel:WORD_1 src1_sel:DWORD
	v_add3_u32 v239, v65, v239, s26
	v_add3_u32 v238, v64, v238, s26
	v_and_b32_e32 v239, 0xffff0000, v239
	v_or_b32_sdwa v225, v239, v238 dst_sel:DWORD dst_unused:UNUSED_PAD src0_sel:DWORD src1_sel:WORD_1
	v_and_b32_e32 v238, 0xffff0000, v238
	v_pk_add_f32 v[240:241], v[64:65], v[238:239] neg_lo:[0,1] neg_hi:[0,1]
	v_cvt_pk_bf16_f32 v229, v240, v241
.LBB0_223:
	s_waitcnt vmcnt(0)
	s_and_b32 s10, s40, 0x8000
	v_add3_u32 v160, v112, v23, s10
	v_add3_u32 v161, v112, v95, s10
	v_add3_u32 v162, v112, v110, s10
	v_add3_u32 v163, v112, v111, s10
	ds_read_b64 v[164:165], v160
	ds_read_b64 v[166:167], v161
	ds_read_b64 v[168:169], v160 offset:2048
	ds_read_b64 v[170:171], v161 offset:2048
	ds_read_b64 v[172:173], v160 offset:4096
	ds_read_b64 v[174:175], v161 offset:4096
	ds_read_b64 v[176:177], v160 offset:6144
	ds_read_b64 v[178:179], v161 offset:6144
	s_add_i32 s36, s41, 0xe0000001
	s_and_b64 s[10:11], s[4:5], exec
	s_cselect_b32 s44, s45, s36
	s_add_i32 s43, s45, 1
	s_and_b64 s[10:11], s[4:5], exec
	s_cselect_b32 s10, s43, s41
	s_cmp_lt_u32 s43, s38
	s_cselect_b32 s10, s10, s44
	s_add_i32 s10, s10, s39
	s_lshl_b32 s10, s10, 3
	s_or_b32 s10, s10, s42
	v_mad_i64_i32 v[2:3], s[46:47], s10, v200, v[90:91]
	v_lshlrev_b32_e32 v130, 2, v26
	v_lshl_add_u64 v[4:5], v[2:3], 0, v[130:131]
	global_load_dword v113, v[4:5], off
	v_lshl_add_u64 v[4:5], v[56:57], 2, v[2:3]
	global_load_dword v114, v[4:5], off
	v_lshl_add_u64 v[4:5], v[54:55], 2, v[2:3]
	global_load_dword v115, v[4:5], off
	v_lshl_add_u64 v[4:5], v[52:53], 2, v[2:3]
	global_load_dword v116, v[4:5], off
	v_lshl_add_u64 v[4:5], v[50:51], 2, v[2:3]
	global_load_dword v117, v[4:5], off
	v_lshl_add_u64 v[4:5], v[48:49], 2, v[2:3]
	global_load_dword v118, v[4:5], off
	v_lshl_add_u64 v[4:5], v[46:47], 2, v[2:3]
	global_load_dword v119, v[4:5], off
	v_lshl_add_u64 v[4:5], v[44:45], 2, v[2:3]
	global_load_dword v121, v[4:5], off
	v_lshl_add_u64 v[4:5], v[42:43], 2, v[2:3]
	global_load_dword v122, v[4:5], off
	v_lshl_add_u64 v[4:5], v[40:41], 2, v[2:3]
	global_load_dword v124, v[4:5], off
	v_lshl_add_u64 v[4:5], v[38:39], 2, v[2:3]
	global_load_dword v127, v[4:5], off
	v_lshl_add_u64 v[4:5], v[36:37], 2, v[2:3]
	s_ashr_i32 s11, s10, 31
	global_load_dword v128, v[4:5], off
	v_lshl_add_u64 v[4:5], v[34:35], 2, v[2:3]
	s_lshl_b64 s[36:37], s[10:11], 2
	global_load_dword v129, v[4:5], off
	v_lshl_add_u64 v[4:5], v[32:33], 2, v[2:3]
	s_add_u32 s36, s86, s36
	global_load_dword v133, v[4:5], off
	v_lshl_add_u64 v[4:5], v[30:31], 2, v[2:3]
	v_lshl_add_u64 v[2:3], v[28:29], 2, v[2:3]
	s_addc_u32 s37, s87, s37
	global_load_dword v135, v[4:5], off
	global_load_dword v142, v[2:3], off
	global_load_dword v143, v131, s[36:37]
	s_cmp_ge_u32 s43, s38
	s_cbranch_scc1 .LBB0_225
	s_mul_hi_i32 s11, s10, 0xc000
	s_mul_i32 s10, s10, 0xc000
	s_add_u32 s10, s68, s10
	s_addc_u32 s11, s69, s11
	v_lshl_add_u64 v[2:3], s[10:11], 0, v[74:75]
	s_mov_b64 s[10:11], 0x4000
	v_lshl_add_u64 v[2:3], v[2:3], 0, s[10:11]
	s_add_i32 s10, s40, 0x8000
	s_and_b32 s10, s10, 0x8000
	v_add_u32_e32 v8, s10, v27
	v_add_u32_e32 v9, 0x400, v8
	v_readfirstlane_b32 s10, v8
	v_lshl_add_u64 v[4:5], v[2:3], 0, v[76:77]
	s_mov_b32 m0, s10
	v_readfirstlane_b32 s10, v9
	global_load_lds_dwordx4 v[4:5], off
	v_lshl_add_u64 v[6:7], v[4:5], 0, s[90:91]
	s_mov_b32 m0, s10
	s_mov_b64 s[10:11], 0x800
	v_add_u32_e32 v9, 0x800, v8
	global_load_lds_dwordx4 v[6:7], off
	v_lshl_add_u64 v[6:7], v[4:5], 0, s[10:11]
	v_readfirstlane_b32 s10, v9
	s_mov_b32 m0, s10
	s_mov_b64 s[10:11], 0xc00
	global_load_lds_dwordx4 v[6:7], off
	v_add_u32_e32 v6, 0xc00, v8
	v_lshl_add_u64 v[4:5], v[4:5], 0, s[10:11]
	v_readfirstlane_b32 s10, v6
	v_add_u32_e32 v6, 0x1000, v8
	s_mov_b32 m0, s10
	v_readfirstlane_b32 s10, v6
	v_add_u32_e32 v6, 0x1400, v8
	global_load_lds_dwordx4 v[4:5], off
	v_lshl_add_u64 v[4:5], v[2:3], 0, v[80:81]
	s_mov_b32 m0, s10
	v_readfirstlane_b32 s10, v6
	v_add_u32_e32 v6, 0x1800, v8
	global_load_lds_dwordx4 v[4:5], off
	v_lshl_add_u64 v[4:5], v[2:3], 0, v[82:83]
	s_mov_b32 m0, s10
	v_readfirstlane_b32 s10, v6
	global_load_lds_dwordx4 v[4:5], off
	v_lshl_add_u64 v[4:5], v[2:3], 0, v[84:85]
	s_mov_b32 m0, s10
	v_lshl_add_u64 v[2:3], v[2:3], 0, v[88:89]
	global_load_lds_dwordx4 v[4:5], off
	v_add_u32_e32 v4, 0x1c00, v8
	s_nop 0
	v_readfirstlane_b32 s10, v4
	s_mov_b32 m0, s10
	s_nop 0
	global_load_lds_dwordx4 v[2:3], off
.LBB0_225:
	v_readlane_b32 s10, v253, 24
	v_readlane_b32 s11, v253, 25
	s_lshl_b64 s[100:101], s[6:7], 14
	s_mul_i32 s36, s6, 0xc000
	s_mul_hi_i32 s37, s6, 0xc000
	s_add_u32 s10, s10, s100
	s_addc_u32 s11, s11, s101
	s_add_u32 s36, s68, s36
	s_addc_u32 s37, s69, s37
	s_waitcnt lgkmcnt(7)
	ds_read_b64 v[180:181], v160 offset:8192
	ds_read_b64 v[182:183], v161 offset:8192
	ds_read_b64 v[184:185], v160 offset:10240
	ds_read_b64 v[186:187], v161 offset:10240
	ds_read_b64 v[188:189], v160 offset:12288
	ds_read_b64 v[190:191], v161 offset:12288
	ds_read_b64 v[192:193], v160 offset:14336
	ds_read_b64 v[194:195], v161 offset:14336
	v_and_b32_sdwa v239, v67, v1 dst_sel:DWORD dst_unused:UNUSED_PAD src0_sel:WORD_1 src1_sel:DWORD
	v_and_b32_sdwa v238, v66, v1 dst_sel:DWORD dst_unused:UNUSED_PAD src0_sel:WORD_1 src1_sel:DWORD
	v_add3_u32 v239, v67, v239, s26
	v_add3_u32 v238, v66, v238, s26
	v_and_b32_e32 v239, 0xffff0000, v239
	v_or_b32_sdwa v230, v239, v238 dst_sel:DWORD dst_unused:UNUSED_PAD src0_sel:DWORD src1_sel:WORD_1
	v_and_b32_e32 v238, 0xffff0000, v238
	v_pk_add_f32 v[240:241], v[66:67], v[238:239] neg_lo:[0,1] neg_hi:[0,1]
	v_cvt_pk_bf16_f32 v234, v240, v241
	v_and_b32_sdwa v243, v69, v1 dst_sel:DWORD dst_unused:UNUSED_PAD src0_sel:WORD_1 src1_sel:DWORD
	v_and_b32_sdwa v242, v68, v1 dst_sel:DWORD dst_unused:UNUSED_PAD src0_sel:WORD_1 src1_sel:DWORD
	v_add3_u32 v243, v69, v243, s26
	v_add3_u32 v242, v68, v242, s26
	v_and_b32_e32 v243, 0xffff0000, v243
	v_or_b32_sdwa v231, v243, v242 dst_sel:DWORD dst_unused:UNUSED_PAD src0_sel:DWORD src1_sel:WORD_1
	v_and_b32_e32 v242, 0xffff0000, v242
	v_pk_add_f32 v[244:245], v[68:69], v[242:243] neg_lo:[0,1] neg_hi:[0,1]
	v_cvt_pk_bf16_f32 v235, v244, v245
	s_waitcnt lgkmcnt(7)
	ds_read_b64 v[206:207], v162
	ds_read_b64 v[208:209], v163
	ds_read_b64 v[210:211], v162 offset:2048
	ds_read_b64 v[212:213], v163 offset:2048
	ds_read_b64 v[214:215], v162 offset:4096
	ds_read_b64 v[216:217], v163 offset:4096
	ds_read_b64 v[218:219], v162 offset:6144
	ds_read_b64 v[220:221], v163 offset:6144
	v_and_b32_sdwa v247, v71, v1 dst_sel:DWORD dst_unused:UNUSED_PAD src0_sel:WORD_1 src1_sel:DWORD
	v_and_b32_sdwa v246, v70, v1 dst_sel:DWORD dst_unused:UNUSED_PAD src0_sel:WORD_1 src1_sel:DWORD
	v_add3_u32 v247, v71, v247, s26
	v_add3_u32 v246, v70, v246, s26
	v_and_b32_e32 v247, 0xffff0000, v247
	v_or_b32_sdwa v232, v247, v246 dst_sel:DWORD dst_unused:UNUSED_PAD src0_sel:DWORD src1_sel:WORD_1
	v_and_b32_e32 v246, 0xffff0000, v246
	v_pk_add_f32 v[248:249], v[70:71], v[246:247] neg_lo:[0,1] neg_hi:[0,1]
	v_cvt_pk_bf16_f32 v236, v248, v249
	v_and_b32_sdwa v239, v73, v1 dst_sel:DWORD dst_unused:UNUSED_PAD src0_sel:WORD_1 src1_sel:DWORD
	v_and_b32_sdwa v238, v72, v1 dst_sel:DWORD dst_unused:UNUSED_PAD src0_sel:WORD_1 src1_sel:DWORD
	v_add3_u32 v239, v73, v239, s26
	v_add3_u32 v238, v72, v238, s26
	v_and_b32_e32 v239, 0xffff0000, v239
	v_or_b32_sdwa v233, v239, v238 dst_sel:DWORD dst_unused:UNUSED_PAD src0_sel:DWORD src1_sel:WORD_1
	v_and_b32_e32 v238, 0xffff0000, v238
	v_pk_add_f32 v[240:241], v[72:73], v[238:239] neg_lo:[0,1] neg_hi:[0,1]
	v_cvt_pk_bf16_f32 v237, v240, v241
	v_mfma_f32_16x16x32_bf16 v[2:5], v[164:167], v[222:225], 0
	global_store_dword v196, v159, s[10:11]
	global_store_dword v196, v78, s[36:37]
	v_mfma_f32_16x16x32_bf16 v[6:9], v[168:171], v[222:225], 0
	global_store_dword v196, v158, s[10:11] offset:256
	global_store_dword v196, v79, s[36:37] offset:256
	v_mfma_f32_16x16x32_bf16 v[10:13], v[172:175], v[222:225], 0
	global_store_dword v196, v157, s[10:11] offset:512
	global_store_dword v196, v102, s[36:37] offset:512
	v_mfma_f32_16x16x32_bf16 v[14:17], v[176:179], v[222:225], 0
	global_store_dword v196, v156, s[10:11] offset:768
	global_store_dword v196, v103, s[36:37] offset:768
	v_mfma_f32_16x16x32_bf16 v[2:5], v[164:167], v[226:229], v[2:5]
	global_store_dword v205, v155, s[10:11]
	global_store_dword v205, v106, s[36:37]
	v_mfma_f32_16x16x32_bf16 v[6:9], v[168:171], v[226:229], v[6:9]
	global_store_dword v205, v154, s[10:11] offset:256
	global_store_dword v205, v107, s[36:37] offset:256
	v_mfma_f32_16x16x32_bf16 v[10:13], v[172:175], v[226:229], v[10:13]
	global_store_dword v205, v153, s[10:11] offset:512
	global_store_dword v205, v98, s[36:37] offset:512
	v_mfma_f32_16x16x32_bf16 v[14:17], v[176:179], v[226:229], v[14:17]
	global_store_dword v205, v152, s[10:11] offset:768
	global_store_dword v205, v99, s[36:37] offset:768
	s_waitcnt lgkmcnt(14)
	v_mfma_f32_16x16x32_bf16 v[2:5], v[180:183], v[222:225], v[2:5]
	s_waitcnt lgkmcnt(7)
	ds_read_b64 v[164:165], v162 offset:8192
	ds_read_b64 v[166:167], v163 offset:8192
	global_store_dword v201, v151, s[10:11]
	v_mfma_f32_16x16x32_bf16 v[6:9], v[184:187], v[222:225], v[6:9]
	ds_read_b64 v[168:169], v162 offset:10240
	ds_read_b64 v[170:171], v163 offset:10240
	global_store_dword v201, v108, s[36:37]
	v_mfma_f32_16x16x32_bf16 v[10:13], v[188:191], v[222:225], v[10:13]
	ds_read_b64 v[172:173], v162 offset:12288
	ds_read_b64 v[174:175], v163 offset:12288
	global_store_dword v201, v150, s[10:11] offset:256
	v_mfma_f32_16x16x32_bf16 v[14:17], v[192:195], v[222:225], v[14:17]
	ds_read_b64 v[176:177], v162 offset:14336
	ds_read_b64 v[178:179], v163 offset:14336
	global_store_dword v201, v109, s[36:37] offset:256
	s_waitcnt lgkmcnt(14)
	v_mfma_f32_16x16x32_bf16 v[2:5], v[206:209], v[230:233], v[2:5]
	s_waitcnt lgkmcnt(7)
	ds_read_b64 v[180:181], v160 offset:16384
	ds_read_b64 v[182:183], v161 offset:16384
	global_store_dword v201, v149, s[10:11] offset:512
	global_store_dword v201, v100, s[36:37] offset:512
	v_mfma_f32_16x16x32_bf16 v[6:9], v[210:213], v[230:233], v[6:9]
	ds_read_b64 v[184:185], v160 offset:18432
	ds_read_b64 v[186:187], v161 offset:18432
	global_store_dword v201, v148, s[10:11] offset:768
	global_store_dword v201, v101, s[36:37] offset:768
	v_mfma_f32_16x16x32_bf16 v[2:5], v[206:209], v[234:237], v[2:5]
	ds_read_b64 v[188:189], v160 offset:20480
	ds_read_b64 v[190:191], v161 offset:20480
	global_store_dword v202, v147, s[10:11]
	global_store_dword v202, v104, s[36:37]
	v_mfma_f32_16x16x32_bf16 v[6:9], v[210:213], v[234:237], v[6:9]
	ds_read_b64 v[192:193], v160 offset:22528
	ds_read_b64 v[194:195], v161 offset:22528
	global_store_dword v202, v146, s[10:11] offset:256
	global_store_dword v202, v105, s[36:37] offset:256
	s_waitcnt lgkmcnt(14)
	v_mfma_f32_16x16x32_bf16 v[2:5], v[164:167], v[230:233], v[2:5]
	global_store_dword v202, v145, s[10:11] offset:512
	global_store_dword v202, v96, s[36:37] offset:512
	s_waitcnt lgkmcnt(12)
	v_mfma_f32_16x16x32_bf16 v[6:9], v[168:171], v[230:233], v[6:9]
	global_store_dword v202, v144, s[10:11] offset:768
	global_store_dword v202, v97, s[36:37] offset:768
	v_mfma_f32_16x16x32_bf16 v[10:13], v[214:217], v[230:233], v[10:13]
	s_nop 0
	v_sub_f32_e32 v78, v138, v2
	v_sub_f32_e32 v79, v139, v3
	v_sub_f32_e32 v102, v140, v4
	v_sub_f32_e32 v103, v141, v5
	v_mfma_f32_16x16x32_bf16 v[14:17], v[218:221], v[230:233], v[14:17]
	v_sub_f32_e32 v106, v18, v6
	v_sub_f32_e32 v107, v19, v7
	v_sub_f32_e32 v98, v20, v8
	v_sub_f32_e32 v99, v21, v9
	v_mfma_f32_16x16x32_bf16 v[10:13], v[214:217], v[234:237], v[10:13]
	v_and_b32_sdwa v239, v79, v1 dst_sel:DWORD dst_unused:UNUSED_PAD src0_sel:WORD_1 src1_sel:DWORD
	v_and_b32_sdwa v238, v78, v1 dst_sel:DWORD dst_unused:UNUSED_PAD src0_sel:WORD_1 src1_sel:DWORD
	v_add3_u32 v239, v79, v239, s26
	v_add3_u32 v238, v78, v238, s26
	v_mfma_f32_16x16x32_bf16 v[14:17], v[218:221], v[234:237], v[14:17]
	v_and_b32_e32 v239, 0xffff0000, v239
	v_or_b32_sdwa v222, v239, v238 dst_sel:DWORD dst_unused:UNUSED_PAD src0_sel:DWORD src1_sel:WORD_1
	v_and_b32_e32 v238, 0xffff0000, v238
	v_pk_add_f32 v[240:241], v[78:79], v[238:239] neg_lo:[0,1] neg_hi:[0,1]
	s_waitcnt lgkmcnt(7)
	ds_read_b64 v[206:207], v160 offset:24576
	ds_read_b64 v[208:209], v161 offset:24576
	ds_read_b64 v[210:211], v160 offset:26624
	ds_read_b64 v[212:213], v161 offset:26624
	ds_read_b64 v[214:215], v160 offset:28672
	ds_read_b64 v[216:217], v161 offset:28672
	ds_read_b64 v[218:219], v160 offset:30720
	ds_read_b64 v[220:221], v161 offset:30720
	v_mfma_f32_16x16x32_bf16 v[10:13], v[172:175], v[230:233], v[10:13]
	v_cvt_pk_bf16_f32 v226, v240, v241
	v_and_b32_sdwa v243, v103, v1 dst_sel:DWORD dst_unused:UNUSED_PAD src0_sel:WORD_1 src1_sel:DWORD
	v_and_b32_sdwa v242, v102, v1 dst_sel:DWORD dst_unused:UNUSED_PAD src0_sel:WORD_1 src1_sel:DWORD
	v_add3_u32 v243, v103, v243, s26
	v_mfma_f32_16x16x32_bf16 v[14:17], v[176:179], v[230:233], v[14:17]
	v_add3_u32 v242, v102, v242, s26
	v_and_b32_e32 v243, 0xffff0000, v243
	v_or_b32_sdwa v223, v243, v242 dst_sel:DWORD dst_unused:UNUSED_PAD src0_sel:DWORD src1_sel:WORD_1
	v_and_b32_e32 v242, 0xffff0000, v242
	v_pk_add_f32 v[244:245], v[102:103], v[242:243] neg_lo:[0,1] neg_hi:[0,1]
	v_cvt_pk_bf16_f32 v227, v244, v245
	v_and_b32_sdwa v247, v107, v1 dst_sel:DWORD dst_unused:UNUSED_PAD src0_sel:WORD_1 src1_sel:DWORD
	v_and_b32_sdwa v246, v106, v1 dst_sel:DWORD dst_unused:UNUSED_PAD src0_sel:WORD_1 src1_sel:DWORD
	v_add3_u32 v247, v107, v247, s26
	v_add3_u32 v246, v106, v246, s26
	v_and_b32_e32 v247, 0xffff0000, v247
	v_or_b32_sdwa v224, v247, v246 dst_sel:DWORD dst_unused:UNUSED_PAD src0_sel:DWORD src1_sel:WORD_1
	v_and_b32_e32 v246, 0xffff0000, v246
	v_pk_add_f32 v[248:249], v[106:107], v[246:247] neg_lo:[0,1] neg_hi:[0,1]
	v_cvt_pk_bf16_f32 v228, v248, v249
	v_and_b32_sdwa v239, v99, v1 dst_sel:DWORD dst_unused:UNUSED_PAD src0_sel:WORD_1 src1_sel:DWORD
	v_and_b32_sdwa v238, v98, v1 dst_sel:DWORD dst_unused:UNUSED_PAD src0_sel:WORD_1 src1_sel:DWORD
	v_add3_u32 v239, v99, v239, s26
	v_add3_u32 v238, v98, v238, s26
	v_and_b32_e32 v239, 0xffff0000, v239
	v_or_b32_sdwa v225, v239, v238 dst_sel:DWORD dst_unused:UNUSED_PAD src0_sel:DWORD src1_sel:WORD_1
	v_and_b32_e32 v238, 0xffff0000, v238
	v_pk_add_f32 v[240:241], v[98:99], v[238:239] neg_lo:[0,1] neg_hi:[0,1]
	v_cvt_pk_bf16_f32 v229, v240, v241
	v_pk_mul_f32 v[2:3], v[94:95], v[60:61] op_sel_hi:[0,1]
	v_pk_mul_f32 v[4:5], v[94:95], v[58:59] op_sel_hi:[0,1]
	v_pk_mul_f32 v[6:7], v[94:95], v[62:63] op_sel_hi:[0,1]
	v_pk_mul_f32 v[8:9], v[94:95], v[64:65] op_sel_hi:[0,1]
	s_add_i32 s44, s44, s39
	s_lshl_b32 s6, s44, 3
	s_or_b32 s6, s6, s42
	s_ashr_i32 s7, s6, 31
	s_add_i32 s41, s41, -1
	s_add_i32 s40, s40, 0x8000
	v_sub_f32_e32 v108, v132, v10
	v_sub_f32_e32 v109, v134, v11
	v_sub_f32_e32 v100, v136, v12
	v_sub_f32_e32 v101, v137, v13
	v_sub_f32_e32 v104, v120, v14
	v_sub_f32_e32 v105, v123, v15
	v_sub_f32_e32 v96, v125, v16
	v_sub_f32_e32 v97, v126, v17
	v_pk_mul_f32 v[10:11], v[94:95], v[66:67] op_sel_hi:[0,1]
	v_pk_mul_f32 v[12:13], v[94:95], v[68:69] op_sel_hi:[0,1]
	v_pk_mul_f32 v[14:15], v[94:95], v[70:71] op_sel_hi:[0,1]
	v_pk_mul_f32 v[16:17], v[94:95], v[72:73] op_sel_hi:[0,1]
	s_waitcnt lgkmcnt(7)
	ds_read_b64 v[164:165], v162 offset:16384
	ds_read_b64 v[166:167], v163 offset:16384
	ds_read_b64 v[168:169], v162 offset:18432
	ds_read_b64 v[170:171], v163 offset:18432
	ds_read_b64 v[172:173], v162 offset:20480
	ds_read_b64 v[174:175], v163 offset:20480
	ds_read_b64 v[176:177], v162 offset:22528
	ds_read_b64 v[178:179], v163 offset:22528
	v_mfma_f32_16x16x32_bf16 v[2:5], v[180:183], v[222:225], v[2:5]
	v_and_b32_sdwa v239, v109, v1 dst_sel:DWORD dst_unused:UNUSED_PAD src0_sel:WORD_1 src1_sel:DWORD
	v_and_b32_sdwa v238, v108, v1 dst_sel:DWORD dst_unused:UNUSED_PAD src0_sel:WORD_1 src1_sel:DWORD
	v_add3_u32 v239, v109, v239, s26
	v_mfma_f32_16x16x32_bf16 v[6:9], v[184:187], v[222:225], v[6:9]
	v_add3_u32 v238, v108, v238, s26
	v_and_b32_e32 v239, 0xffff0000, v239
	v_or_b32_sdwa v230, v239, v238 dst_sel:DWORD dst_unused:UNUSED_PAD src0_sel:DWORD src1_sel:WORD_1
	v_mfma_f32_16x16x32_bf16 v[10:13], v[188:191], v[222:225], v[10:13]
	v_and_b32_e32 v238, 0xffff0000, v238
	v_pk_add_f32 v[240:241], v[108:109], v[238:239] neg_lo:[0,1] neg_hi:[0,1]
	v_cvt_pk_bf16_f32 v234, v240, v241
	v_mfma_f32_16x16x32_bf16 v[14:17], v[192:195], v[222:225], v[14:17]
	v_and_b32_sdwa v243, v101, v1 dst_sel:DWORD dst_unused:UNUSED_PAD src0_sel:WORD_1 src1_sel:DWORD
	v_and_b32_sdwa v242, v100, v1 dst_sel:DWORD dst_unused:UNUSED_PAD src0_sel:WORD_1 src1_sel:DWORD
	v_add3_u32 v243, v101, v243, s26
	v_mfma_f32_16x16x32_bf16 v[2:5], v[180:183], v[226:229], v[2:5]
	v_add3_u32 v242, v100, v242, s26
	v_and_b32_e32 v243, 0xffff0000, v243
	v_or_b32_sdwa v231, v243, v242 dst_sel:DWORD dst_unused:UNUSED_PAD src0_sel:DWORD src1_sel:WORD_1
	v_mfma_f32_16x16x32_bf16 v[6:9], v[184:187], v[226:229], v[6:9]
	v_and_b32_e32 v242, 0xffff0000, v242
	v_pk_add_f32 v[244:245], v[100:101], v[242:243] neg_lo:[0,1] neg_hi:[0,1]
	v_cvt_pk_bf16_f32 v235, v244, v245
	v_mfma_f32_16x16x32_bf16 v[10:13], v[188:191], v[226:229], v[10:13]
	v_and_b32_sdwa v247, v105, v1 dst_sel:DWORD dst_unused:UNUSED_PAD src0_sel:WORD_1 src1_sel:DWORD
	v_and_b32_sdwa v246, v104, v1 dst_sel:DWORD dst_unused:UNUSED_PAD src0_sel:WORD_1 src1_sel:DWORD
	v_add3_u32 v247, v105, v247, s26
	v_mfma_f32_16x16x32_bf16 v[14:17], v[192:195], v[226:229], v[14:17]
	v_add3_u32 v246, v104, v246, s26
	v_and_b32_e32 v247, 0xffff0000, v247
	v_or_b32_sdwa v232, v247, v246 dst_sel:DWORD dst_unused:UNUSED_PAD src0_sel:DWORD src1_sel:WORD_1
	s_waitcnt lgkmcnt(7)
	ds_read_b64 v[180:181], v162 offset:24576
	ds_read_b64 v[182:183], v163 offset:24576
	v_mfma_f32_16x16x32_bf16 v[2:5], v[206:209], v[222:225], v[2:5]
	v_and_b32_e32 v246, 0xffff0000, v246
	v_pk_add_f32 v[248:249], v[104:105], v[246:247] neg_lo:[0,1] neg_hi:[0,1]
	v_cvt_pk_bf16_f32 v236, v248, v249
	ds_read_b64 v[184:185], v162 offset:26624
	ds_read_b64 v[186:187], v163 offset:26624
	v_mfma_f32_16x16x32_bf16 v[6:9], v[210:213], v[222:225], v[6:9]
	v_and_b32_sdwa v239, v97, v1 dst_sel:DWORD dst_unused:UNUSED_PAD src0_sel:WORD_1 src1_sel:DWORD
	v_and_b32_sdwa v238, v96, v1 dst_sel:DWORD dst_unused:UNUSED_PAD src0_sel:WORD_1 src1_sel:DWORD
	v_add3_u32 v239, v97, v239, s26
	ds_read_b64 v[188:189], v162 offset:28672
	ds_read_b64 v[190:191], v163 offset:28672
	v_mfma_f32_16x16x32_bf16 v[10:13], v[214:217], v[222:225], v[10:13]
	v_add3_u32 v238, v96, v238, s26
	v_and_b32_e32 v239, 0xffff0000, v239
	v_or_b32_sdwa v233, v239, v238 dst_sel:DWORD dst_unused:UNUSED_PAD src0_sel:DWORD src1_sel:WORD_1
	ds_read_b64 v[192:193], v162 offset:30720
	ds_read_b64 v[194:195], v163 offset:30720
	v_mfma_f32_16x16x32_bf16 v[14:17], v[218:221], v[222:225], v[14:17]
	v_and_b32_e32 v238, 0xffff0000, v238
	v_pk_add_f32 v[240:241], v[96:97], v[238:239] neg_lo:[0,1] neg_hi:[0,1]
	v_cvt_pk_bf16_f32 v237, v240, v241
	s_waitcnt lgkmcnt(14)
	v_mfma_f32_16x16x32_bf16 v[2:5], v[164:167], v[230:233], v[2:5]
	s_waitcnt lgkmcnt(12)
	v_mfma_f32_16x16x32_bf16 v[6:9], v[168:171], v[230:233], v[6:9]
	v_mfma_f32_16x16x32_bf16 v[2:5], v[164:167], v[234:237], v[2:5]
	v_mfma_f32_16x16x32_bf16 v[6:9], v[168:171], v[234:237], v[6:9]
	s_waitcnt lgkmcnt(6)
	v_mfma_f32_16x16x32_bf16 v[2:5], v[180:183], v[230:233], v[2:5]
	s_waitcnt lgkmcnt(4)
	v_mfma_f32_16x16x32_bf16 v[6:9], v[184:187], v[230:233], v[6:9]
	v_mfma_f32_16x16x32_bf16 v[10:13], v[172:175], v[230:233], v[10:13]
	s_nop 4
	v_and_b32_sdwa v239, v3, v1 dst_sel:DWORD dst_unused:UNUSED_PAD src0_sel:WORD_1 src1_sel:DWORD
	v_and_b32_sdwa v238, v2, v1 dst_sel:DWORD dst_unused:UNUSED_PAD src0_sel:WORD_1 src1_sel:DWORD
	v_add3_u32 v239, v3, v239, s26
	v_add3_u32 v238, v2, v238, s26
	v_mfma_f32_16x16x32_bf16 v[14:17], v[176:179], v[230:233], v[14:17]
	v_and_b32_e32 v239, 0xffff0000, v239
	v_or_b32_sdwa v222, v239, v238 dst_sel:DWORD dst_unused:UNUSED_PAD src0_sel:DWORD src1_sel:WORD_1
	v_and_b32_e32 v238, 0xffff0000, v238
	v_pk_add_f32 v[240:241], v[2:3], v[238:239] neg_lo:[0,1] neg_hi:[0,1]
	v_mfma_f32_16x16x32_bf16 v[10:13], v[172:175], v[234:237], v[10:13]
	v_cvt_pk_bf16_f32 v226, v240, v241
	v_and_b32_sdwa v243, v5, v1 dst_sel:DWORD dst_unused:UNUSED_PAD src0_sel:WORD_1 src1_sel:DWORD
	v_and_b32_sdwa v242, v4, v1 dst_sel:DWORD dst_unused:UNUSED_PAD src0_sel:WORD_1 src1_sel:DWORD
	v_add3_u32 v243, v5, v243, s26
	v_mfma_f32_16x16x32_bf16 v[14:17], v[176:179], v[234:237], v[14:17]
	v_add3_u32 v242, v4, v242, s26
	v_and_b32_e32 v243, 0xffff0000, v243
	v_or_b32_sdwa v223, v243, v242 dst_sel:DWORD dst_unused:UNUSED_PAD src0_sel:DWORD src1_sel:WORD_1
	v_and_b32_e32 v242, 0xffff0000, v242
	s_waitcnt lgkmcnt(2)
	v_mfma_f32_16x16x32_bf16 v[10:13], v[188:191], v[230:233], v[10:13]
	v_pk_add_f32 v[244:245], v[4:5], v[242:243] neg_lo:[0,1] neg_hi:[0,1]
	v_cvt_pk_bf16_f32 v227, v244, v245
	v_and_b32_sdwa v247, v7, v1 dst_sel:DWORD dst_unused:UNUSED_PAD src0_sel:WORD_1 src1_sel:DWORD
	v_and_b32_sdwa v246, v6, v1 dst_sel:DWORD dst_unused:UNUSED_PAD src0_sel:WORD_1 src1_sel:DWORD
	s_waitcnt lgkmcnt(0)
	v_mfma_f32_16x16x32_bf16 v[14:17], v[192:195], v[230:233], v[14:17]
	v_add3_u32 v247, v7, v247, s26
	v_add3_u32 v246, v6, v246, s26
	v_and_b32_e32 v247, 0xffff0000, v247
	v_or_b32_sdwa v224, v247, v246 dst_sel:DWORD dst_unused:UNUSED_PAD src0_sel:DWORD src1_sel:WORD_1
	v_and_b32_e32 v246, 0xffff0000, v246
	v_pk_add_f32 v[248:249], v[6:7], v[246:247] neg_lo:[0,1] neg_hi:[0,1]
	v_cvt_pk_bf16_f32 v228, v248, v249
	v_and_b32_sdwa v239, v9, v1 dst_sel:DWORD dst_unused:UNUSED_PAD src0_sel:WORD_1 src1_sel:DWORD
	v_and_b32_sdwa v238, v8, v1 dst_sel:DWORD dst_unused:UNUSED_PAD src0_sel:WORD_1 src1_sel:DWORD
	v_add3_u32 v239, v9, v239, s26
	v_add3_u32 v238, v8, v238, s26
	v_and_b32_e32 v239, 0xffff0000, v239
	v_or_b32_sdwa v225, v239, v238 dst_sel:DWORD dst_unused:UNUSED_PAD src0_sel:DWORD src1_sel:WORD_1
	v_and_b32_e32 v238, 0xffff0000, v238
	v_pk_add_f32 v[240:241], v[8:9], v[238:239] neg_lo:[0,1] neg_hi:[0,1]
	v_cvt_pk_bf16_f32 v229, v240, v241
	s_waitcnt vmcnt(32)
	s_cmp_eq_u32 s43, s38
	s_barrier
	s_cbranch_scc1 .LBB0_229
	v_mov_b32_e32 v94, v143
	s_mov_b32 s45, s43
	v_mov_b32_e32 v159, v60
	v_mov_b32_e32 v158, v61
	v_mov_b32_e32 v157, v58
	v_mov_b32_e32 v156, v59
	v_mov_b32_e32 v155, v62
	v_mov_b32_e32 v154, v63
	v_mov_b32_e32 v153, v64
	v_mov_b32_e32 v152, v65
	v_mov_b32_e32 v151, v66
	v_mov_b32_e32 v150, v67
	v_mov_b32_e32 v149, v68
	v_mov_b32_e32 v148, v69
	v_mov_b32_e32 v147, v70
	v_mov_b32_e32 v146, v71
	v_mov_b32_e32 v145, v72
	v_mov_b32_e32 v144, v73
	v_mov_b32_e32 v138, v113
	v_mov_b32_e32 v139, v114
	v_mov_b32_e32 v140, v115
	v_mov_b32_e32 v141, v116
	v_mov_b32_e32 v18, v117
	v_mov_b32_e32 v19, v118
	v_mov_b32_e32 v20, v119
	v_mov_b32_e32 v21, v121
	v_mov_b32_e32 v132, v122
	v_mov_b32_e32 v134, v124
	v_mov_b32_e32 v136, v127
	v_mov_b32_e32 v137, v128
	v_mov_b32_e32 v120, v129
	v_mov_b32_e32 v123, v133
	v_mov_b32_e32 v125, v135
	v_mov_b32_e32 v126, v142
	v_mov_b32_e32 v60, v2
	v_mov_b32_e32 v61, v3
	v_mov_b32_e32 v58, v4
	v_mov_b32_e32 v59, v5
	v_mov_b32_e32 v62, v6
	v_mov_b32_e32 v63, v7
	v_mov_b32_e32 v64, v8
	v_mov_b32_e32 v65, v9
	v_mov_b32_e32 v66, v10
	v_mov_b32_e32 v67, v11
	v_mov_b32_e32 v68, v12
	v_mov_b32_e32 v69, v13
	v_mov_b32_e32 v70, v14
	v_mov_b32_e32 v71, v15
	v_mov_b32_e32 v72, v16
	v_mov_b32_e32 v73, v17
	s_branch .LBB0_223
